# on top of v198: nt hint also on the WIN-tail stores of the transposed f2u weights (first read at GU2)
# baseline (speedup 1.0000x reference)
.LBB0_905:
	s_lshl_b32 s16, s15, 1
	s_lshl_b32 s17, s14, 1
	v_or_b32_e32 v11, s16, v1
	v_or_b32_e32 v13, s17, v2
	s_add_i32 s18, s16, 4
	s_add_i32 s19, s17, 4
	s_add_i32 s26, s16, 8
	s_add_i32 s27, s17, 8
	s_add_i32 s28, s16, 12
	s_add_i32 s29, s17, 12
	s_add_i32 s30, s16, 16
	s_add_i32 s31, s17, 16
	s_add_i32 s33, s16, 20
	s_add_i32 s35, s17, 20
	s_add_i32 s52, s16, 24
	s_add_i32 s53, s17, 24
	s_add_i32 s16, s16, 28
	s_add_i32 s17, s17, 28
	v_add_u32_e32 v15, v11, v3
	v_add_u32_e32 v22, v13, v10
	v_or_b32_e32 v54, s18, v1
	v_or_b32_e32 v55, s19, v2
	v_or_b32_e32 v56, s26, v1
	v_or_b32_e32 v57, s27, v2
	v_or_b32_e32 v58, s28, v1
	v_or_b32_e32 v59, s29, v2
	v_or_b32_e32 v60, s30, v1
	v_or_b32_e32 v61, s31, v2
	v_or_b32_e32 v62, s33, v1
	v_or_b32_e32 v63, s35, v2
	v_or_b32_e32 v64, s52, v1
	v_or_b32_e32 v65, s53, v2
	v_or_b32_e32 v66, s16, v1
	v_or_b32_e32 v67, s17, v2
	v_mad_i64_i32 v[22:23], s[16:17], v22, s10, v[16:17]
	v_mad_i64_i32 v[24:25], s[16:17], v15, s10, v[16:17]
	v_add_u32_e32 v15, v54, v3
	v_add_u32_e32 v26, v55, v10
	v_add_u32_e32 v32, v56, v3
	v_add_u32_e32 v30, v57, v10
	v_add_u32_e32 v36, v58, v3
	v_add_u32_e32 v34, v59, v10
	v_add_u32_e32 v40, v60, v3
	v_add_u32_e32 v38, v61, v10
	v_add_u32_e32 v44, v62, v3
	v_add_u32_e32 v42, v63, v10
	v_add_u32_e32 v48, v64, v3
	v_add_u32_e32 v46, v65, v10
	v_add_u32_e32 v52, v66, v3
	v_add_u32_e32 v50, v67, v10
	v_mad_i64_i32 v[26:27], s[16:17], v26, s10, v[16:17]
	v_mad_i64_i32 v[28:29], s[16:17], v15, s10, v[16:17]
	v_mad_i64_i32 v[30:31], s[16:17], v30, s10, v[16:17]
	v_mad_i64_i32 v[32:33], s[16:17], v32, s10, v[16:17]
	v_mad_i64_i32 v[34:35], s[16:17], v34, s10, v[16:17]
	v_mad_i64_i32 v[36:37], s[16:17], v36, s10, v[16:17]
	v_mad_i64_i32 v[38:39], s[16:17], v38, s10, v[16:17]
	v_mad_i64_i32 v[40:41], s[16:17], v40, s10, v[16:17]
	v_mad_i64_i32 v[42:43], s[16:17], v42, s10, v[16:17]
	v_mad_i64_i32 v[44:45], s[16:17], v44, s10, v[16:17]
	v_mad_i64_i32 v[46:47], s[16:17], v46, s10, v[16:17]
	v_mad_i64_i32 v[48:49], s[16:17], v48, s10, v[16:17]
	v_mad_i64_i32 v[50:51], s[16:17], v50, s10, v[16:17]
	v_mad_i64_i32 v[52:53], s[16:17], v52, s10, v[16:17]
	global_load_dword v15, v[22:23], off nt
	global_load_dword v68, v[24:25], off nt
	global_load_dword v69, v[26:27], off nt
	global_load_dword v70, v[28:29], off nt
	global_load_dword v71, v[30:31], off nt
	global_load_dword v72, v[32:33], off nt
	global_load_dword v73, v[34:35], off nt
	global_load_dword v74, v[36:37], off nt
	global_load_dword v75, v[38:39], off nt
	global_load_dword v76, v[40:41], off nt
	global_load_dword v77, v[42:43], off nt
	global_load_dword v78, v[44:45], off nt
	global_load_dword v79, v[46:47], off nt
	global_load_dword v80, v[48:49], off nt
	global_load_dword v81, v[50:51], off nt
	global_load_dword v82, v[52:53], off nt
	s_add_i32 s14, s14, 16
	s_add_i32 s15, s15, 16
	s_add_i32 s13, s13, -16
	v_mad_u64_u32 v[22:23], s[16:17], v13, s5, v[4:5]
	s_cmp_lg_u32 s13, 0
	v_mad_u64_u32 v[24:25], s[16:17], v11, s5, v[4:5]
	v_mad_u64_u32 v[26:27], s[16:17], v55, s5, v[4:5]
	v_mad_u64_u32 v[28:29], s[16:17], v54, s5, v[4:5]
	v_mad_u64_u32 v[30:31], s[16:17], v57, s5, v[4:5]
	v_mad_u64_u32 v[32:33], s[16:17], v56, s5, v[4:5]
	v_mad_u64_u32 v[34:35], s[16:17], v59, s5, v[4:5]
	v_mad_u64_u32 v[36:37], s[16:17], v58, s5, v[4:5]
	v_mad_u64_u32 v[38:39], s[16:17], v61, s5, v[4:5]
	v_mad_u64_u32 v[40:41], s[16:17], v60, s5, v[4:5]
	v_mad_u64_u32 v[42:43], s[16:17], v63, s5, v[4:5]
	v_mad_u64_u32 v[44:45], s[16:17], v62, s5, v[4:5]
	v_mad_u64_u32 v[46:47], s[16:17], v65, s5, v[4:5]
	v_mad_u64_u32 v[48:49], s[16:17], v64, s5, v[4:5]
	v_mad_u64_u32 v[50:51], s[16:17], v67, s5, v[4:5]
	v_mad_u64_u32 v[52:53], s[16:17], v66, s5, v[4:5]
	s_waitcnt vmcnt(15)
	ds_write_b32 v22, v15
	s_waitcnt vmcnt(14)
	ds_write_b32 v24, v68
	s_waitcnt vmcnt(13)
	ds_write_b32 v26, v69
	s_waitcnt vmcnt(12)
	ds_write_b32 v28, v70
	s_waitcnt vmcnt(11)
	ds_write_b32 v30, v71
	s_waitcnt vmcnt(10)
	ds_write_b32 v32, v72
	s_waitcnt vmcnt(9)
	ds_write_b32 v34, v73
	s_waitcnt vmcnt(8)
	ds_write_b32 v36, v74
	s_waitcnt vmcnt(7)
	ds_write_b32 v38, v75
	s_waitcnt vmcnt(6)
	ds_write_b32 v40, v76
	s_waitcnt vmcnt(5)
	ds_write_b32 v42, v77
	s_waitcnt vmcnt(4)
	ds_write_b32 v44, v78
	s_waitcnt vmcnt(3)
	ds_write_b32 v46, v79
	s_waitcnt vmcnt(2)
	ds_write_b32 v48, v80
	s_waitcnt vmcnt(1)
	ds_write_b32 v50, v81
	s_waitcnt vmcnt(0)
	ds_write_b32 v52, v82
	s_cbranch_scc1 .LBB0_905
	v_lshlrev_b32_e32 v3, 6, v12
	s_waitcnt lgkmcnt(0)
	v_and_b32_e32 v3, 0xffffff00, v3
	v_and_b32_e32 v11, 0x60, v14
	ds_read2_b32 v[14:15], v18 offset0:33 offset1:41
	ds_read2_b32 v[16:17], v18 offset1:8
	ds_read2_b32 v[22:23], v18 offset0:66 offset1:74
	ds_read2_b32 v[24:25], v18 offset0:99 offset1:107
	ds_read2_b32 v[26:27], v18 offset0:132 offset1:140
	ds_read2_b32 v[28:29], v18 offset0:165 offset1:173
	ds_read2_b32 v[30:31], v18 offset0:198 offset1:206
	ds_read2_b32 v[32:33], v18 offset0:231 offset1:239
	v_or3_b32 v3, v11, v3, s11
	v_or_b32_e32 v36, v3, v5
	v_ashrrev_i32_e32 v11, 31, v10
	v_ashrrev_i32_e32 v37, 31, v36
	v_lshl_add_u64 v[34:35], v[10:11], 1, v[8:9]
	v_lshlrev_b64 v[36:37], 12, v[36:37]
	s_waitcnt lgkmcnt(6)
	v_cvt_pk_bf16_f32 v10, v16, v14
	s_waitcnt lgkmcnt(4)
	v_cvt_pk_bf16_f32 v11, v22, v24
	s_waitcnt lgkmcnt(2)
	v_cvt_pk_bf16_f32 v12, v26, v28
	s_waitcnt lgkmcnt(0)
	v_cvt_pk_bf16_f32 v13, v30, v32
	v_lshl_add_u64 v[36:37], v[34:35], 0, v[36:37]
	v_or_b32_e32 v14, v3, v19
	global_store_dwordx4 v[36:37], v[10:13], off nt
	v_add_u32_e32 v0, s4, v0
	v_cmp_lt_i32_e32 vcc, s12, v0
	v_cvt_pk_bf16_f32 v10, v17, v15
	v_ashrrev_i32_e32 v15, 31, v14
	v_cvt_pk_bf16_f32 v11, v23, v25
	v_cvt_pk_bf16_f32 v12, v27, v29
	v_cvt_pk_bf16_f32 v13, v31, v33
	v_lshlrev_b64 v[14:15], 12, v[14:15]
	ds_read2_b32 v[16:17], v18 offset0:49 offset1:57
	ds_read2_b32 v[22:23], v18 offset0:16 offset1:24
	ds_read2_b32 v[24:25], v18 offset0:82 offset1:90
	ds_read2_b32 v[26:27], v18 offset0:115 offset1:123
	ds_read2_b32 v[28:29], v18 offset0:148 offset1:156
	ds_read2_b32 v[30:31], v18 offset0:181 offset1:189
	ds_read2_b32 v[32:33], v18 offset0:214 offset1:222
	ds_read2_b32 v[36:37], v18 offset0:247 offset1:255
	v_lshl_add_u64 v[14:15], v[34:35], 0, v[14:15]
	global_store_dwordx4 v[14:15], v[10:13], off nt
	v_or_b32_e32 v14, v3, v20
	v_ashrrev_i32_e32 v15, 31, v14
	v_lshlrev_b64 v[14:15], 12, v[14:15]
	s_waitcnt lgkmcnt(6)
	v_cvt_pk_bf16_f32 v10, v22, v16
	s_waitcnt lgkmcnt(4)
	v_cvt_pk_bf16_f32 v11, v24, v26
	s_waitcnt lgkmcnt(2)
	v_cvt_pk_bf16_f32 v12, v28, v30
	s_waitcnt lgkmcnt(0)
	v_cvt_pk_bf16_f32 v13, v32, v36
	v_lshl_add_u64 v[14:15], v[34:35], 0, v[14:15]
	global_store_dwordx4 v[14:15], v[10:13], off nt
	v_or_b32_e32 v14, v3, v21
	v_ashrrev_i32_e32 v15, 31, v14
	v_lshlrev_b64 v[14:15], 12, v[14:15]
	v_cvt_pk_bf16_f32 v10, v23, v17
	v_cvt_pk_bf16_f32 v11, v25, v27
	v_cvt_pk_bf16_f32 v12, v29, v31
	v_cvt_pk_bf16_f32 v13, v33, v37
	v_lshl_add_u64 v[14:15], v[34:35], 0, v[14:15]
	global_store_dwordx4 v[14:15], v[10:13], off nt
	s_waitcnt lgkmcnt(0)
	s_or_b64 s[2:3], vcc, s[2:3]
	s_andn2_b64 exec, exec, s[2:3]
	s_cbranch_execnz .LBB0_904

.LT_da_done:
	s_mul_i32 s87, s87, s72
	s_lshl_b32 s84, s84, 7
	s_add_u32 s87, s87, s84
	s_add_u32 s82, s54, s87
	s_addc_u32 s83, s55, 0
	global_load_dwordx4 v[80:83], v36, s[80:81] nt
	global_load_dwordx4 v[84:87], v37, s[80:81] nt
	global_load_dwordx4 v[88:91], v38, s[80:81] nt
	global_load_dwordx4 v[92:95], v39, s[80:81] nt
	global_load_dwordx4 v[96:99], v40, s[80:81] nt
	global_load_dwordx4 v[100:103], v41, s[80:81] nt
	global_load_dwordx4 v[104:107], v42, s[80:81] nt
	global_load_dwordx4 v[108:111], v43, s[80:81] nt
	s_waitcnt vmcnt(8)
	v_cvt_pk_bf16_f32 v112, v48, v52
	v_cvt_pk_bf16_f32 v113, v56, v60
	v_cvt_pk_bf16_f32 v114, v64, v68
	v_cvt_pk_bf16_f32 v115, v72, v76
	v_cvt_pk_bf16_f32 v116, v49, v53
	v_cvt_pk_bf16_f32 v117, v57, v61
	v_cvt_pk_bf16_f32 v118, v65, v69
	v_cvt_pk_bf16_f32 v119, v73, v77
	v_cvt_pk_bf16_f32 v120, v50, v54
	v_cvt_pk_bf16_f32 v121, v58, v62
	v_cvt_pk_bf16_f32 v122, v66, v70
	v_cvt_pk_bf16_f32 v123, v74, v78
	v_cvt_pk_bf16_f32 v124, v51, v55
	v_cvt_pk_bf16_f32 v125, v59, v63
	v_cvt_pk_bf16_f32 v126, v67, v71
	v_cvt_pk_bf16_f32 v127, v75, v79
	global_store_dwordx4 v44, v[112:115], s[58:59] nt
	global_store_dwordx4 v45, v[116:119], s[58:59] nt
	global_store_dwordx4 v46, v[120:123], s[58:59] nt
	global_store_dwordx4 v47, v[124:127], s[58:59] nt
	s_add_u32 s65, s65, s66
	s_cmp_ge_u32 s65, s68
	s_cbranch_scc1 .LT_lastB
	s_mul_hi_u32 s84, s65, s69
	s_mul_i32 s85, s84, s70
	s_sub_u32 s85, s65, s85
	s_mul_i32 s86, s84, s77
	s_lshl_b32 s87, s85, 7
	s_add_u32 s86, s86, s87
	s_add_u32 s56, s52, s86
	s_addc_u32 s57, s53, 0
	s_lshl_b32 s87, s85, 5
	s_cmp_eq_u32 s73, 0
	s_cbranch_scc1 .LT_db_done
	s_cmp_eq_u32 s73, 1
	s_cbranch_scc0 .LT_db_win
	s_lshr_b32 s87, s85, 2
	s_lshl_b32 s87, s87, 8
	s_and_b32 s88, s85, 3
	s_lshl_b32 s88, s88, 5
	s_add_u32 s87, s87, s88
	s_add_u32 s87, s87, s74
	s_branch .LT_db_done

.LT_db_done:
	s_mul_i32 s87, s87, s72
	s_lshl_b32 s84, s84, 7
	s_add_u32 s87, s87, s84
	s_add_u32 s58, s54, s87
	s_addc_u32 s59, s55, 0
	global_load_dwordx4 v[48:51], v36, s[56:57] nt
	global_load_dwordx4 v[52:55], v37, s[56:57] nt
	global_load_dwordx4 v[56:59], v38, s[56:57] nt
	global_load_dwordx4 v[60:63], v39, s[56:57] nt
	global_load_dwordx4 v[64:67], v40, s[56:57] nt
	global_load_dwordx4 v[68:71], v41, s[56:57] nt
	global_load_dwordx4 v[72:75], v42, s[56:57] nt
	global_load_dwordx4 v[76:79], v43, s[56:57] nt
	s_waitcnt vmcnt(8)
	v_cvt_pk_bf16_f32 v112, v80, v84
	v_cvt_pk_bf16_f32 v113, v88, v92
	v_cvt_pk_bf16_f32 v114, v96, v100
	v_cvt_pk_bf16_f32 v115, v104, v108
	v_cvt_pk_bf16_f32 v116, v81, v85
	v_cvt_pk_bf16_f32 v117, v89, v93
	v_cvt_pk_bf16_f32 v118, v97, v101
	v_cvt_pk_bf16_f32 v119, v105, v109
	v_cvt_pk_bf16_f32 v120, v82, v86
	v_cvt_pk_bf16_f32 v121, v90, v94
	v_cvt_pk_bf16_f32 v122, v98, v102
	v_cvt_pk_bf16_f32 v123, v106, v110
	v_cvt_pk_bf16_f32 v124, v83, v87
	v_cvt_pk_bf16_f32 v125, v91, v95
	v_cvt_pk_bf16_f32 v126, v99, v103
	v_cvt_pk_bf16_f32 v127, v107, v111
	global_store_dwordx4 v44, v[112:115], s[82:83] nt
	global_store_dwordx4 v45, v[116:119], s[82:83] nt
	global_store_dwordx4 v46, v[120:123], s[82:83] nt
	global_store_dwordx4 v47, v[124:127], s[82:83] nt
	s_branch .LT_loop
.LT_lastA:
	s_waitcnt vmcnt(0)
	v_cvt_pk_bf16_f32 v112, v48, v52
	v_cvt_pk_bf16_f32 v113, v56, v60
	v_cvt_pk_bf16_f32 v114, v64, v68
	v_cvt_pk_bf16_f32 v115, v72, v76
	v_cvt_pk_bf16_f32 v116, v49, v53
	v_cvt_pk_bf16_f32 v117, v57, v61
	v_cvt_pk_bf16_f32 v118, v65, v69
	v_cvt_pk_bf16_f32 v119, v73, v77
	v_cvt_pk_bf16_f32 v120, v50, v54
	v_cvt_pk_bf16_f32 v121, v58, v62
	v_cvt_pk_bf16_f32 v122, v66, v70
	v_cvt_pk_bf16_f32 v123, v74, v78
	v_cvt_pk_bf16_f32 v124, v51, v55
	v_cvt_pk_bf16_f32 v125, v59, v63
	v_cvt_pk_bf16_f32 v126, v67, v71
	v_cvt_pk_bf16_f32 v127, v75, v79
	global_store_dwordx4 v44, v[112:115], s[58:59] nt
	global_store_dwordx4 v45, v[116:119], s[58:59] nt
	global_store_dwordx4 v46, v[120:123], s[58:59] nt
	global_store_dwordx4 v47, v[124:127], s[58:59] nt
	s_branch .LT_done
.LT_lastB:
	s_waitcnt vmcnt(0)
	v_cvt_pk_bf16_f32 v112, v80, v84
	v_cvt_pk_bf16_f32 v113, v88, v92
	v_cvt_pk_bf16_f32 v114, v96, v100
	v_cvt_pk_bf16_f32 v115, v104, v108
	v_cvt_pk_bf16_f32 v116, v81, v85
	v_cvt_pk_bf16_f32 v117, v89, v93
	v_cvt_pk_bf16_f32 v118, v97, v101
	v_cvt_pk_bf16_f32 v119, v105, v109
	v_cvt_pk_bf16_f32 v120, v82, v86
	v_cvt_pk_bf16_f32 v121, v90, v94
	v_cvt_pk_bf16_f32 v122, v98, v102
	v_cvt_pk_bf16_f32 v123, v106, v110
	v_cvt_pk_bf16_f32 v124, v83, v87
	v_cvt_pk_bf16_f32 v125, v91, v95
	v_cvt_pk_bf16_f32 v126, v99, v103
	v_cvt_pk_bf16_f32 v127, v107, v111
	global_store_dwordx4 v44, v[112:115], s[82:83] nt
	global_store_dwordx4 v45, v[116:119], s[82:83] nt
	global_store_dwordx4 v46, v[120:123], s[82:83] nt
	global_store_dwordx4 v47, v[124:127], s[82:83] nt
